# v120 + P2 inverse levels: all MFMA operands of a level fetched from LDS up front (batched) instead of one round trip per f32 MFMA
# speedup vs baseline: 1.0166x; 1.0034x over previous
; #define LAS __attribute__((address_space(3)))
; template <int SKIP>
; __device__ __forceinline__ void p2_chunk_prep_fast(Frame& F, const Args& a) {
;     ...
;         for (int dd = 1; dd < 4; ++dd) {
;             if (w < 4 - dd && !(SKIP & 8)) {
;                 const int bb = w, ab = w + dd;
;                 f32x4 acc = (f32x4){0.f, 0.f, 0.f, 0.f};
;                 for (int c = bb; c < ab; ++c)
; #pragma unroll
;                     for (int ks = 0; ks < 4; ++ks) acc = __builtin_amdgcn_mfma_f32_16x16x4f32(Am[(16 * ab + fr) * AM_LD + 16 * c + 4 * ks + fq], Tm[(16 * c + 4 * ks + fq) * AM_LD + 16 * bb + fr], acc, 0, 0, 0);
;                 LAS float* Xs = (LAS float*)(L + L_XS + w * 1152);
; #pragma unroll
;                 for (int r = 0; r < 4; ++r) Xs[(4 * fq + r) * 17 + fr] = acc[r];
;                 f32x4 acc2 = (f32x4){0.f, 0.f, 0.f, 0.f};
; #pragma unroll
;                 for (int ks = 0; ks < 4; ++ks) acc2 = __builtin_amdgcn_mfma_f32_16x16x4f32(Tm[(16 * ab + fr) * AM_LD + 16 * ab + 4 * ks + fq], Xs[(4 * ks + fq) * 17 + fr], acc2, 0, 0, 0);
; #pragma unroll
;                 for (int r = 0; r < 4; ++r) Tm[(16 * ab + 4 * fq + r) * AM_LD + 16 * bb + fr] = -acc2[r];
;             }
;             __syncthreads();
.LBB0_709:
	v_lshl_add_u32 v47, v118, 2, s29
	v_add_u32_e32 v46, s56, v70
	v_add_u32_e32 v48, s57, v70
	s_andn2_b64 vcc, exec, s[82:83]
	v_add_u32_e32 v50, s54, v118
	s_waitcnt lgkmcnt(0)
	s_barrier
	s_cbranch_vccnz .Lkd_slot1
	v_or_b32_e32 v49, s33, v83
	v_mul_lo_u32 v49, v49, s28
	s_lshl_b32 s6, s54, 2
	v_add3_u32 v51, v47, v49, s6
	v_mad_u64_u32 v[58:59], s[6:7], v50, s28, v[46:47]
	ds_read2_b32 v[152:153], v51 offset1:4
	ds_read2_b32 v[154:155], v51 offset0:8 offset1:12
	ds_read_b32 v156, v58
	ds_read_b32 v157, v58 offset:1088
	ds_read_b32 v158, v58 offset:2176
	ds_read_b32 v159, v58 offset:3264
	v_mad_u64_u32 v[60:61], s[6:7], v118, s28, v[48:49]
	s_lshl_b32 s6, s33, 2
	v_add_u32_e32 v49, s60, v49
	v_add3_u32 v49, v49, v67, s6
	s_movk_i32 s6, 0x44
	ds_read2_b32 v[160:161], v49 offset1:4
	ds_read2_b32 v[162:163], v49 offset0:8 offset1:12
	v_mad_u64_u32 v[58:59], s[6:7], v118, s6, v[48:49]
	s_waitcnt lgkmcnt(2)
	v_mfma_f32_16x16x4_f32 v[52:55], v152, v156, 0
	v_mfma_f32_16x16x4_f32 v[52:55], v153, v157, v[52:55]
	v_mfma_f32_16x16x4_f32 v[52:55], v154, v158, v[52:55]
	v_mfma_f32_16x16x4_f32 v[52:55], v155, v159, v[52:55]
	v_add_u32_e32 v49, s33, v67
	v_mad_u64_u32 v[56:57], s[6:7], v49, s28, v[46:47]
	s_nop 7
	ds_write2_b32 v60, v52, v53 offset1:17
	ds_write2_b32 v60, v54, v55 offset0:34 offset1:51
	ds_read2_b32 v[164:165], v58 offset1:68
	ds_read2_b32 v[166:167], v58 offset0:136 offset1:204
	s_waitcnt lgkmcnt(0)
	v_mfma_f32_16x16x4_f32 v[52:55], v160, v164, 0
	v_mfma_f32_16x16x4_f32 v[52:55], v161, v165, v[52:55]
	v_mfma_f32_16x16x4_f32 v[52:55], v162, v166, v[52:55]
	v_mfma_f32_16x16x4_f32 v[52:55], v163, v167, v[52:55]
	s_nop 9
	v_xor_b32_e32 v49, 0x80000000, v52
	v_xor_b32_e32 v51, 0x80000000, v53
	v_xor_b32_e32 v52, 0x80000000, v54
	v_xor_b32_e32 v53, 0x80000000, v55
	ds_write2_b32 v56, v49, v51 offset1:68
	ds_write2_b32 v56, v52, v53 offset0:136 offset1:204
	s_branch .LBB0_711

; #define LAS __attribute__((address_space(3)))
; template <int SKIP>
; __device__ __forceinline__ void p2_chunk_prep_fast(Frame& F, const Args& a) {
;     ...
;         for (int dd = 1; dd < 4; ++dd) {
;             if (w < 4 - dd && !(SKIP & 8)) {
;                 const int bb = w, ab = w + dd;
;                 f32x4 acc = (f32x4){0.f, 0.f, 0.f, 0.f};
;                 for (int c = bb; c < ab; ++c)
; #pragma unroll
;                     for (int ks = 0; ks < 4; ++ks) acc = __builtin_amdgcn_mfma_f32_16x16x4f32(Am[(16 * ab + fr) * AM_LD + 16 * c + 4 * ks + fq], Tm[(16 * c + 4 * ks + fq) * AM_LD + 16 * bb + fr], acc, 0, 0, 0);
;                 LAS float* Xs = (LAS float*)(L + L_XS + w * 1152);
; #pragma unroll
;                 for (int r = 0; r < 4; ++r) Xs[(4 * fq + r) * 17 + fr] = acc[r];
;                 f32x4 acc2 = (f32x4){0.f, 0.f, 0.f, 0.f};
; #pragma unroll
;                 for (int ks = 0; ks < 4; ++ks) acc2 = __builtin_amdgcn_mfma_f32_16x16x4f32(Tm[(16 * ab + fr) * AM_LD + 16 * ab + 4 * ks + fq], Xs[(4 * ks + fq) * 17 + fr], acc2, 0, 0, 0);
; #pragma unroll
;                 for (int r = 0; r < 4; ++r) Tm[(16 * ab + 4 * fq + r) * AM_LD + 16 * bb + fr] = -acc2[r];
;             }
;             __syncthreads();
.LBB0_711:
	s_andn2_b64 vcc, exec, s[2:3]
	v_add_u32_e32 v49, s33, v118
	s_waitcnt lgkmcnt(0)
	s_barrier
	s_cbranch_vccnz .Lkd_slot2
	v_or_b32_e32 v51, s10, v83
	v_mul_lo_u32 v58, v51, s28
	s_lshl_b32 s6, s54, 2
	v_add3_u32 v59, v47, v58, s6
	v_mad_u64_u32 v[56:57], s[6:7], v50, s28, v[46:47]
	v_mad_u64_u32 v[54:55], s[6:7], v49, s28, v[46:47]
	ds_read2_b32 v[152:153], v59 offset1:4
	ds_read2_b32 v[154:155], v59 offset0:8 offset1:12
	ds_read2_b32 v[156:157], v59 offset0:16 offset1:20
	ds_read2_b32 v[158:159], v59 offset0:24 offset1:28
	ds_read_b32 v160, v56
	ds_read_b32 v161, v56 offset:1088
	ds_read_b32 v162, v56 offset:2176
	ds_read_b32 v163, v56 offset:3264
	ds_read_b32 v164, v54
	ds_read_b32 v165, v54 offset:1088
	ds_read_b32 v166, v54 offset:2176
	ds_read_b32 v167, v54 offset:3264
	v_mad_u64_u32 v[60:61], s[6:7], v118, s28, v[48:49]
	s_lshl_b32 s6, s10, 2
	v_add_u32_e32 v55, s60, v58
	v_add3_u32 v62, v55, v67, s6
	s_movk_i32 s6, 0x44
	ds_read2_b32 v[168:169], v62 offset1:4
	ds_read2_b32 v[170:171], v62 offset0:8 offset1:12
	v_mad_u64_u32 v[56:57], s[6:7], v118, s6, v[48:49]
	s_waitcnt lgkmcnt(2)
	v_mfma_f32_16x16x4_f32 v[172:175], v152, v160, 0
	v_mfma_f32_16x16x4_f32 v[172:175], v153, v161, v[172:175]
	v_mfma_f32_16x16x4_f32 v[172:175], v154, v162, v[172:175]
	v_mfma_f32_16x16x4_f32 v[172:175], v155, v163, v[172:175]
	v_mfma_f32_16x16x4_f32 v[172:175], v156, v164, v[172:175]
	v_mfma_f32_16x16x4_f32 v[172:175], v157, v165, v[172:175]
	v_mfma_f32_16x16x4_f32 v[172:175], v158, v166, v[172:175]
	v_mfma_f32_16x16x4_f32 v[172:175], v159, v167, v[172:175]
	v_add_u32_e32 v54, s10, v67
	v_mad_u64_u32 v[54:55], s[6:7], v54, s28, v[46:47]
	s_nop 7
	ds_write2_b32 v60, v172, v173 offset1:17
	ds_write2_b32 v60, v174, v175 offset0:34 offset1:51
	ds_read2_b32 v[176:177], v56 offset1:68
	ds_read2_b32 v[178:179], v56 offset0:136 offset1:204
	s_waitcnt lgkmcnt(0)
	v_mfma_f32_16x16x4_f32 v[172:175], v168, v176, 0
	v_mfma_f32_16x16x4_f32 v[172:175], v169, v177, v[172:175]
	v_mfma_f32_16x16x4_f32 v[172:175], v170, v178, v[172:175]
	v_mfma_f32_16x16x4_f32 v[172:175], v171, v179, v[172:175]
	s_nop 9
	v_xor_b32_e32 v50, 0x80000000, v172
	v_xor_b32_e32 v51, 0x80000000, v173
	v_xor_b32_e32 v52, 0x80000000, v174
	v_xor_b32_e32 v53, 0x80000000, v175
	ds_write2_b32 v54, v50, v51 offset1:68
	ds_write2_b32 v54, v52, v53 offset0:136 offset1:204
	s_branch .LBB0_713

; #define LAS __attribute__((address_space(3)))
; template <int SKIP>
; __device__ __forceinline__ void p2_chunk_prep_fast(Frame& F, const Args& a) {
;     ...
;         for (int dd = 1; dd < 4; ++dd) {
;             if (w < 4 - dd && !(SKIP & 8)) {
;                 const int bb = w, ab = w + dd;
;                 f32x4 acc = (f32x4){0.f, 0.f, 0.f, 0.f};
;                 for (int c = bb; c < ab; ++c)
; #pragma unroll
;                     for (int ks = 0; ks < 4; ++ks) acc = __builtin_amdgcn_mfma_f32_16x16x4f32(Am[(16 * ab + fr) * AM_LD + 16 * c + 4 * ks + fq], Tm[(16 * c + 4 * ks + fq) * AM_LD + 16 * bb + fr], acc, 0, 0, 0);
;                 LAS float* Xs = (LAS float*)(L + L_XS + w * 1152);
; #pragma unroll
;                 for (int r = 0; r < 4; ++r) Xs[(4 * fq + r) * 17 + fr] = acc[r];
;                 f32x4 acc2 = (f32x4){0.f, 0.f, 0.f, 0.f};
; #pragma unroll
;                 for (int ks = 0; ks < 4; ++ks) acc2 = __builtin_amdgcn_mfma_f32_16x16x4f32(Tm[(16 * ab + fr) * AM_LD + 16 * ab + 4 * ks + fq], Xs[(4 * ks + fq) * 17 + fr], acc2, 0, 0, 0);
; #pragma unroll
;                 for (int r = 0; r < 4; ++r) Tm[(16 * ab + 4 * fq + r) * AM_LD + 16 * bb + fr] = -acc2[r];
;             }
;             __syncthreads();
.LBB0_713:
	s_andn2_b64 vcc, exec, s[50:51]
	s_waitcnt lgkmcnt(0)
	s_barrier
	s_cbranch_vccnz .Lkd_slot3
	v_mul_u32_u24_e32 v58, 0x110, v83
	s_lshl_b32 s6, s54, 2
	v_add3_u32 v47, v47, v58, s6
	v_add_u32_e32 v47, 0x3000, v47
	v_mul_lo_u32 v59, v118, s28
	v_add_u32_e32 v56, v46, v59
	v_mad_u64_u32 v[54:55], s[6:7], v49, s28, v[46:47]
	v_add_u32_e32 v60, s10, v118
	v_mad_u64_u32 v[60:61], s[6:7], v60, s28, v[46:47]
	ds_read2_b32 v[152:153], v47 offset0:192 offset1:196
	ds_read2_b32 v[154:155], v47 offset0:200 offset1:204
	ds_read2_b32 v[156:157], v47 offset0:208 offset1:212
	ds_read2_b32 v[158:159], v47 offset0:216 offset1:220
	ds_read2_b32 v[160:161], v47 offset0:224 offset1:228
	ds_read2_b32 v[162:163], v47 offset0:232 offset1:236
	ds_read_b32 v164, v56
	ds_read_b32 v165, v56 offset:1088
	ds_read_b32 v166, v56 offset:2176
	ds_read_b32 v167, v56 offset:3264
	ds_read_b32 v168, v54
	ds_read_b32 v169, v54 offset:1088
	ds_read_b32 v170, v54 offset:2176
	ds_read_b32 v171, v54 offset:3264
	ds_read_b32 v172, v60
	ds_read_b32 v173, v60 offset:1088
	ds_read_b32 v174, v60 offset:2176
	ds_read_b32 v175, v60 offset:3264
	v_readlane_b32 s6, v255, 53
	v_add_u32_e32 v49, v48, v59
	s_nop 1
	v_add3_u32 v62, s6, v58, v67
	v_add_u32_e32 v62, 0x3000, v62
	ds_read2_b32 v[176:177], v62 offset0:192 offset1:196
	ds_read2_b32 v[178:179], v62 offset0:200 offset1:204
	s_movk_i32 s6, 0x44
	v_mad_u64_u32 v[54:55], s[6:7], v118, s6, v[48:49]
	s_waitcnt lgkmcnt(2)
	v_mfma_f32_16x16x4_f32 v[180:183], v152, v164, 0
	v_mfma_f32_16x16x4_f32 v[180:183], v153, v165, v[180:183]
	v_mfma_f32_16x16x4_f32 v[180:183], v154, v166, v[180:183]
	v_mfma_f32_16x16x4_f32 v[180:183], v155, v167, v[180:183]
	v_mfma_f32_16x16x4_f32 v[180:183], v156, v168, v[180:183]
	v_mfma_f32_16x16x4_f32 v[180:183], v157, v169, v[180:183]
	v_mfma_f32_16x16x4_f32 v[180:183], v158, v170, v[180:183]
	v_mfma_f32_16x16x4_f32 v[180:183], v159, v171, v[180:183]
	v_mfma_f32_16x16x4_f32 v[180:183], v160, v172, v[180:183]
	v_mfma_f32_16x16x4_f32 v[180:183], v161, v173, v[180:183]
	v_mfma_f32_16x16x4_f32 v[180:183], v162, v174, v[180:183]
	v_mfma_f32_16x16x4_f32 v[180:183], v163, v175, v[180:183]
	v_readlane_b32 s6, v255, 51
	s_nop 1
	v_add_u32_e32 v47, s6, v67
	v_mad_u64_u32 v[46:47], s[6:7], v47, s28, v[46:47]
	s_nop 4
	ds_write2_b32 v49, v180, v181 offset1:17
	ds_write2_b32 v49, v182, v183 offset0:34 offset1:51
	ds_read2_b32 v[184:185], v54 offset1:68
	ds_read2_b32 v[186:187], v54 offset0:136 offset1:204
	s_waitcnt lgkmcnt(0)
	v_mfma_f32_16x16x4_f32 v[180:183], v176, v184, 0
	v_mfma_f32_16x16x4_f32 v[180:183], v177, v185, v[180:183]
	v_mfma_f32_16x16x4_f32 v[180:183], v178, v186, v[180:183]
	v_mfma_f32_16x16x4_f32 v[180:183], v179, v187, v[180:183]
	s_nop 9
	v_xor_b32_e32 v188, 0x80000000, v180
	v_xor_b32_e32 v189, 0x80000000, v181
	v_xor_b32_e32 v190, 0x80000000, v182
	v_xor_b32_e32 v191, 0x80000000, v183
	ds_write2_b32 v46, v188, v189 offset1:68
	ds_write2_b32 v46, v190, v191 offset0:136 offset1:204
	s_branch .LBB0_715
